# PH0: the 160 fifth weight-copy items move from 20 weight workgroups (the phase's last arrivers) to 20 GEMV workgroups with slack
# baseline (speedup 1.0000x reference)
.LBB0_56:
	s_andn2_b64 vcc, exec, s[0:1]
	s_cbranch_vccnz .LBB0_77
	s_cmpk_lt_i32 s96, 0xc0
	s_cbranch_scc0 .Lw0_norm
	s_cmp_gt_u32 s96, 22
	s_cbranch_scc1 .LBB0_77
	s_and_b32 s0, s96, 7
	s_cmp_eq_u32 s0, 0
	s_cbranch_scc1 .LBB0_77
	s_lshr_b32 s0, s96, 3
	s_sub_i32 s0, s96, s0
	s_add_i32 s0, s0, -1
	s_lshl_b32 s0, s0, 3
	s_add_i32 s0, s0, 0xe00
	s_branch .Lw0_go
.Lw0_norm:
	s_lshl_b32 s0, s96, 3
.Lw0_go:
	s_add_i32 s0, s0, s86
	s_add_i32 s11, s0, 0xfffffa00
	s_cmpk_gt_i32 s11, 0x89f
	s_cbranch_scc1 .LBB0_77
	v_lshlrev_b32_e32 v0, 2, v12
	v_ashrrev_i32_e32 v4, 3, v12
	v_and_b32_e32 v0, 28, v0
	s_movk_i32 s1, 0x84
	s_waitcnt lgkmcnt(4)
	v_lshlrev_b32_e32 v2, 3, v12
	s_waitcnt lgkmcnt(3)
	v_lshl_add_u32 v3, v0, 2, s10
	s_waitcnt lgkmcnt(2)
	v_mul_lo_u32 v6, v4, s1
	v_and_b32_e32 v2, 56, v2
	v_mov_b32_e32 v1, 0
	v_mul_u32_u24_e32 v5, 0x84, v2
	s_waitcnt lgkmcnt(1)
	v_lshlrev_b32_e32 v7, 2, v4
	v_add_u32_e32 v6, v3, v6
	v_add3_u32 v5, s10, v5, v7
	s_add_i32 s10, s0, 0xfffff180
	v_lshlrev_b32_e32 v0, 2, v0
	v_add_u32_e32 v7, 0x420, v6
	v_add_u32_e32 v8, 0x428, v6
	s_waitcnt lgkmcnt(0)
	v_add_u32_e32 v9, 0x840, v6
	v_add_u32_e32 v10, 0x848, v6
	v_add_u32_e32 v11, 0xc60, v6
	v_add_u32_e32 v13, 0xc68, v6
	v_add_u32_e32 v16, 0x1080, v6
	v_add_u32_e32 v17, 0x1088, v6
	v_add_u32_e32 v18, 0x14a0, v6
	v_add_u32_e32 v19, 0x14a8, v6
	v_add_u32_e32 v20, 0x18c0, v6
	v_add_u32_e32 v21, 0x18c8, v6
	v_add_u32_e32 v22, 0x1ce0, v6
	v_add_u32_e32 v23, 0x1ce8, v6
	v_lshlrev_b32_e32 v2, 1, v2
	v_mov_b32_e32 v3, v1
	s_movk_i32 s12, 0x7fff
	s_mov_b32 s13, 0xffff0000
	s_branch .LBB0_62

.LBB0_61:
	s_add_u32 s7, s50, s4
	s_addc_u32 s20, s51, s5
	s_lshr_b32 s4, s6, 5
	v_cvt_f32_ubyte0_e32 v24, s4
	v_rcp_iflag_f32_e32 v24, v24
	s_sub_i32 s17, 0, s4
	s_abs_i32 s16, s15
	s_ashr_i32 s5, s15, 31
	v_mul_f32_e32 v24, 0x4f7ffffe, v24
	v_cvt_u32_f32_e32 v24, v24
	s_nop 0
	v_readfirstlane_b32 s18, v24
	s_mul_i32 s17, s17, s18
	s_mul_hi_u32 s17, s18, s17
	s_add_i32 s18, s18, s17
	s_mul_hi_u32 s17, s16, s18
	s_mul_i32 s18, s17, s4
	s_sub_i32 s16, s16, s18
	s_add_i32 s19, s17, 1
	s_sub_i32 s18, s16, s4
	s_cmp_ge_u32 s16, s4
	s_cselect_b32 s17, s19, s17
	s_cselect_b32 s16, s18, s16
	s_add_i32 s18, s17, 1
	s_cmp_ge_u32 s16, s4
	s_cselect_b32 s16, s18, s17
	s_xor_b32 s16, s16, s5
	s_sub_i32 s5, s16, s5
	s_mul_i32 s4, s5, s4
	s_sub_i32 s4, s15, s4
	s_lshl_b32 s4, s4, 5
	s_lshl_b32 s16, s5, 6
	s_ashr_i32 s5, s4, 31
	s_lshl_b64 s[18:19], s[4:5], 2
	v_add_u32_e32 v54, s16, v4
	s_add_u32 s2, s2, s18
	s_addc_u32 s3, s3, s19
	v_add_u32_e32 v26, 8, v54
	v_add_u32_e32 v32, 16, v54
	v_add_u32_e32 v34, 24, v54
	v_add_u32_e32 v40, 32, v54
	v_add_u32_e32 v42, 40, v54
	v_lshl_add_u64 v[52:53], s[2:3], 0, v[0:1]
	v_mad_i64_i32 v[24:25], s[2:3], v54, s6, 0
	v_mad_i64_i32 v[26:27], s[2:3], v26, s6, 0
	v_mad_i64_i32 v[32:33], s[2:3], v32, s6, 0
	v_mad_i64_i32 v[34:35], s[2:3], v34, s6, 0
	v_mad_i64_i32 v[40:41], s[2:3], v40, s6, 0
	v_mad_i64_i32 v[42:43], s[2:3], v42, s6, 0
	v_lshl_add_u64 v[24:25], v[24:25], 2, v[52:53]
	v_lshl_add_u64 v[28:29], v[26:27], 2, v[52:53]
	v_lshl_add_u64 v[32:33], v[32:33], 2, v[52:53]
	v_lshl_add_u64 v[36:37], v[34:35], 2, v[52:53]
	v_lshl_add_u64 v[40:41], v[40:41], 2, v[52:53]
	v_lshl_add_u64 v[44:45], v[42:43], 2, v[52:53]
	global_load_dwordx4 v[24:27], v[24:25], off
	s_nop 0
	global_load_dwordx4 v[28:31], v[28:29], off
	s_nop 0
	global_load_dwordx4 v[32:35], v[32:33], off
	s_nop 0
	global_load_dwordx4 v[36:39], v[36:37], off
	s_nop 0
	global_load_dwordx4 v[40:43], v[40:41], off
	s_nop 0
	global_load_dwordx4 v[44:47], v[44:45], off
	v_add_u32_e32 v48, 48, v54
	v_mad_i64_i32 v[48:49], s[2:3], v48, s6, 0
	v_lshl_add_u64 v[48:49], v[48:49], 2, v[52:53]
	v_add_u32_e32 v54, 56, v54
	global_load_dwordx4 v[48:51], v[48:49], off
	v_mad_i64_i32 v[54:55], s[2:3], v54, s6, 0
	v_lshl_add_u64 v[52:53], v[54:55], 2, v[52:53]
	global_load_dwordx4 v[52:55], v[52:53], off
	s_ashr_i32 s17, s16, 31
	s_lshl_b64 s[2:3], s[16:17], 1
	s_add_u32 s2, s7, s2
	s_addc_u32 s3, s20, s3
	v_lshl_add_u64 v[56:57], s[2:3], 0, v[2:3]
	s_addk_i32 s11, 0x200
	s_addk_i32 s10, 0x200
	s_cmpk_gt_i32 s14, 0x5ff
	s_waitcnt vmcnt(7)
	ds_write2_b32 v6, v24, v25 offset1:1
	ds_write2_b32 v6, v26, v27 offset0:2 offset1:3
	s_waitcnt vmcnt(6)
	ds_write2_b32 v7, v28, v29 offset1:1
	ds_write2_b32 v8, v30, v31 offset1:1
	s_waitcnt vmcnt(5)
	ds_write2_b32 v9, v32, v33 offset1:1
	ds_write2_b32 v10, v34, v35 offset1:1
	s_waitcnt vmcnt(4)
	ds_write2_b32 v11, v36, v37 offset1:1
	ds_write2_b32 v13, v38, v39 offset1:1
	s_waitcnt vmcnt(3)
	ds_write2_b32 v16, v40, v41 offset1:1
	ds_write2_b32 v17, v42, v43 offset1:1
	s_waitcnt vmcnt(2)
	ds_write2_b32 v18, v44, v45 offset1:1
	ds_write2_b32 v19, v46, v47 offset1:1
	s_waitcnt vmcnt(1)
	ds_write2_b32 v20, v48, v49 offset1:1
	ds_write2_b32 v21, v50, v51 offset1:1
	s_waitcnt vmcnt(0)
	ds_write2_b32 v22, v52, v53 offset1:1
	ds_write2_b32 v23, v54, v55 offset1:1
	s_waitcnt lgkmcnt(0)
	ds_read2_b32 v[28:29], v5 offset0:33 offset1:41
	ds_read2_b32 v[30:31], v5 offset1:8
	ds_read2_b32 v[32:33], v5 offset0:66 offset1:74
	ds_read2_b32 v[34:35], v5 offset0:99 offset1:107
	ds_read2_b32 v[36:37], v5 offset0:132 offset1:140
	ds_read2_b32 v[38:39], v5 offset0:165 offset1:173
	ds_read2_b32 v[40:41], v5 offset0:198 offset1:206
	ds_read2_b32 v[42:43], v5 offset0:231 offset1:239
	s_waitcnt lgkmcnt(6)
	v_bfe_u32 v24, v30, 16, 1
	v_bfe_u32 v25, v28, 16, 1
	s_waitcnt lgkmcnt(5)
	v_bfe_u32 v26, v32, 16, 1
	s_waitcnt lgkmcnt(3)
	v_bfe_u32 v44, v36, 16, 1
	v_bfe_u32 v27, v34, 16, 1
	s_waitcnt lgkmcnt(2)
	v_bfe_u32 v45, v38, 16, 1
	s_waitcnt lgkmcnt(1)
	v_bfe_u32 v46, v40, 16, 1
	v_add3_u32 v24, v30, v24, s12
	v_add3_u32 v25, v28, v25, s12
	v_add3_u32 v26, v32, v26, s12
	v_add3_u32 v28, v36, v44, s12
	v_add3_u32 v27, v34, v27, s12
	v_add3_u32 v30, v38, v45, s12
	v_add3_u32 v32, v40, v46, s12
	v_lshrrev_b32_e32 v24, 16, v24
	v_lshrrev_b32_e32 v26, 16, v26
	v_lshrrev_b32_e32 v28, 16, v28
	v_add_u32_e32 v46, s4, v4
	v_and_or_b32 v24, v25, s13, v24
	v_and_or_b32 v25, v27, s13, v26
	v_and_or_b32 v26, v30, s13, v28
	v_ashrrev_i32_e32 v28, 31, v46
	s_waitcnt lgkmcnt(0)
	v_bfe_u32 v27, v42, 16, 1
	v_mul_lo_u32 v28, s0, v28
	v_mul_lo_u32 v30, s1, v46
	v_mad_u64_u32 v[44:45], s[2:3], s0, v46, 0
	v_lshrrev_b32_e32 v32, 16, v32
	v_add3_u32 v27, v42, v27, s12
	v_add3_u32 v45, v45, v28, v30
	v_and_or_b32 v27, v27, s13, v32
	v_lshl_add_u64 v[44:45], v[44:45], 1, v[56:57]
	global_store_dwordx4 v[44:45], v[24:27], off
	v_bfe_u32 v28, v43, 16, 1
	v_add3_u32 v28, v43, v28, s12
	v_bfe_u32 v24, v31, 16, 1
	v_add3_u32 v24, v31, v24, s12
	v_bfe_u32 v25, v29, 16, 1
	v_lshrrev_b32_e32 v24, 16, v24
	v_add3_u32 v25, v29, v25, s12
	v_and_or_b32 v24, v25, s13, v24
	v_bfe_u32 v25, v33, 16, 1
	v_add3_u32 v25, v33, v25, s12
	v_bfe_u32 v26, v35, 16, 1
	v_lshrrev_b32_e32 v25, 16, v25
	v_add3_u32 v26, v35, v26, s12
	v_and_or_b32 v25, v26, s13, v25
	v_bfe_u32 v26, v37, 16, 1
	v_add3_u32 v26, v37, v26, s12
	v_bfe_u32 v27, v39, 16, 1
	v_lshrrev_b32_e32 v26, 16, v26
	v_add3_u32 v27, v39, v27, s12
	v_and_or_b32 v26, v27, s13, v26
	v_bfe_u32 v27, v41, 16, 1
	v_add3_u32 v27, v41, v27, s12
	v_lshrrev_b32_e32 v27, 16, v27
	v_and_or_b32 v27, v28, s13, v27
	v_add_u32_e32 v28, 8, v46
	v_ashrrev_i32_e32 v29, 31, v28
	v_mul_lo_u32 v32, s0, v29
	v_mul_lo_u32 v33, s1, v28
	v_mad_u64_u32 v[28:29], s[2:3], s0, v28, 0
	v_add3_u32 v29, v29, v32, v33
	ds_read2_b32 v[30:31], v5 offset0:16 offset1:24
	v_lshl_add_u64 v[28:29], v[28:29], 1, v[56:57]
	global_store_dwordx4 v[28:29], v[24:27], off
	ds_read2_b32 v[28:29], v5 offset0:49 offset1:57
	ds_read2_b32 v[32:33], v5 offset0:82 offset1:90
	ds_read2_b32 v[34:35], v5 offset0:115 offset1:123
	s_waitcnt lgkmcnt(3)
	v_bfe_u32 v24, v30, 16, 1
	v_add3_u32 v24, v30, v24, s12
	s_waitcnt lgkmcnt(2)
	v_bfe_u32 v25, v28, 16, 1
	ds_read2_b32 v[36:37], v5 offset0:148 offset1:156
	v_lshrrev_b32_e32 v24, 16, v24
	v_add3_u32 v25, v28, v25, s12
	ds_read2_b32 v[38:39], v5 offset0:181 offset1:189
	v_and_or_b32 v24, v25, s13, v24
	s_waitcnt lgkmcnt(3)
	v_bfe_u32 v25, v32, 16, 1
	v_add3_u32 v25, v32, v25, s12
	s_waitcnt lgkmcnt(2)
	v_bfe_u32 v26, v34, 16, 1
	ds_read2_b32 v[40:41], v5 offset0:214 offset1:222
	v_lshrrev_b32_e32 v25, 16, v25
	v_add3_u32 v26, v34, v26, s12
	ds_read2_b32 v[42:43], v5 offset0:247 offset1:255
	v_and_or_b32 v25, v26, s13, v25
	s_waitcnt lgkmcnt(3)
	v_bfe_u32 v26, v36, 16, 1
	v_add3_u32 v26, v36, v26, s12
	s_waitcnt lgkmcnt(2)
	v_bfe_u32 v27, v38, 16, 1
	v_lshrrev_b32_e32 v26, 16, v26
	v_add3_u32 v27, v38, v27, s12
	v_and_or_b32 v26, v27, s13, v26
	s_waitcnt lgkmcnt(1)
	v_bfe_u32 v27, v40, 16, 1
	v_add3_u32 v27, v40, v27, s12
	s_waitcnt lgkmcnt(0)
	v_bfe_u32 v28, v42, 16, 1
	v_lshrrev_b32_e32 v27, 16, v27
	v_add3_u32 v28, v42, v28, s12
	v_and_or_b32 v27, v28, s13, v27
	v_add_u32_e32 v28, 16, v46
	v_ashrrev_i32_e32 v30, 31, v28
	v_mul_lo_u32 v30, s0, v30
	v_mul_lo_u32 v32, s1, v28
	v_mad_u64_u32 v[44:45], s[2:3], s0, v28, 0
	v_add3_u32 v45, v45, v30, v32
	v_lshl_add_u64 v[44:45], v[44:45], 1, v[56:57]
	global_store_dwordx4 v[44:45], v[24:27], off
	v_bfe_u32 v28, v43, 16, 1
	v_add3_u32 v28, v43, v28, s12
	v_bfe_u32 v24, v31, 16, 1
	v_add3_u32 v24, v31, v24, s12
	v_bfe_u32 v25, v29, 16, 1
	v_lshrrev_b32_e32 v24, 16, v24
	v_add3_u32 v25, v29, v25, s12
	v_and_or_b32 v24, v25, s13, v24
	v_bfe_u32 v25, v33, 16, 1
	v_add3_u32 v25, v33, v25, s12
	v_bfe_u32 v26, v35, 16, 1
	v_lshrrev_b32_e32 v25, 16, v25
	v_add3_u32 v26, v35, v26, s12
	v_and_or_b32 v25, v26, s13, v25
	v_bfe_u32 v26, v37, 16, 1
	v_add3_u32 v26, v37, v26, s12
	v_bfe_u32 v27, v39, 16, 1
	v_lshrrev_b32_e32 v26, 16, v26
	v_add3_u32 v27, v39, v27, s12
	v_and_or_b32 v26, v27, s13, v26
	v_bfe_u32 v27, v41, 16, 1
	v_add3_u32 v27, v41, v27, s12
	v_lshrrev_b32_e32 v27, 16, v27
	v_and_or_b32 v27, v28, s13, v27
	v_add_u32_e32 v28, 24, v46
	v_ashrrev_i32_e32 v29, 31, v28
	v_mul_lo_u32 v30, s0, v29
	v_mul_lo_u32 v31, s1, v28
	v_mad_u64_u32 v[28:29], s[0:1], s0, v28, 0
	v_add3_u32 v29, v29, v30, v31
	v_lshl_add_u64 v[28:29], v[28:29], 1, v[56:57]
	global_store_dwordx4 v[28:29], v[24:27], off
	s_waitcnt lgkmcnt(0)
	s_cbranch_scc1 .LBB0_77
